# speedup vs baseline: 1.0123x; 1.0021x over previous
; __device__ __forceinline__ float log_sigmoid(float x) {
;   const float e = __expf(-x);
;   const float poly = e * (1.f - e * (0.5f - e * (0.33333334f - e * (0.25f - e * 0.2f))));
;   return -(e < 0.125f ? poly : __logf(1.f + e));
; }
; __device__ __forceinline__ void ret_scan_phase(const Params& p, int j, float* __restrict__ U) {
;     ...
;   for (int g = gtid; g < 2 * 32 * 4 * 1024; g += gsz) {
;     const int idx8 = g & 1023, h = (g >> 10) & 3, b = (g >> 12) & 31, dir = g >> 17;
;     const float lg = log_sigmoid(dir ? p.ret_dec_b[j * 4 + h] : p.ret_dec_f[j * 4 + h]);
;     const float cdec = __expf(128.f * lg);
;     float S[8];
; #pragma unroll
;     for (int i = 0; i < 8; ++i) S[i] = 0.f;
;     uint4* base = (uint4*)((u16*)U + (((size_t)dir * 32 + b) * 18 * 4 + h) * 8192) + idx8;
; #pragma unroll 6
;     for (int s = 0; s < 18; ++s) {
;       int cc = dir == 0 ? s : (s < 2 ? 1 - s : 19 - s);
;       uint4* ptr = base + (size_t)cc * 4 * 1024;
.LBB0_629:
	s_andn2_saveexec_b64 s[0:1], s[0:1]
	v_mov_b32_e32 v0, 0x3e800000
	v_fmamk_f32 v0, v2, 0xbe4ccccd, v0
	s_mov_b32 s6, 0x3eaaaaab
	v_fma_f32 v0, -v2, v0, s6
	v_fma_f32 v0, -v2, v0, 0.5
	v_fma_f32 v0, -v2, v0, 1.0
	v_mul_f32_e32 v0, v2, v0
	s_or_b64 exec, exec, s[0:1]
	v_mul_f32_e32 v0, 0xc3000000, v0
	v_bfe_u32 v4, v20, 12, 5
	v_ashrrev_i32_e32 v5, 17, v20
	v_mul_f32_e32 v0, 0x3fb8aa3b, v0
	v_exp_f32_e32 v2, v0
	v_lshl_or_b32 v0, v5, 5, v4
	v_mul_hi_i32_i24_e32 v5, 0x48, v0
	v_mul_i32_i24_e32 v0, 0x48, v0
	v_or_b32_e32 v4, v0, v3
	v_and_b32_e32 v6, 0x3ff, v20
	v_lshlrev_b64 v[4:5], 14, v[4:5]
	v_lshl_add_u64 v[4:5], s[76:77], 0, v[4:5]
	v_lshlrev_b32_e32 v0, 4, v6
	v_mov_b32_e32 v12, 0
	v_lshl_add_u64 v[4:5], v[4:5], 0, v[0:1]
	v_mov_b32_e32 v3, v2
	v_mov_b32_e32 v6, v2
	v_mov_b32_e32 v7, v2
	v_mov_b32_e32 v8, v2
	v_mov_b32_e32 v9, v2
	v_mov_b32_e32 v10, v2
	v_mov_b32_e32 v11, v2
	s_mov_b32 s0, 0
	s_mov_b32 s1, 0
	v_mov_b32_e32 v13, v12
	v_mov_b32_e32 v14, v12
	v_mov_b32_e32 v15, v12
	v_mov_b32_e32 v16, v12
	v_mov_b32_e32 v17, v12
	v_mov_b32_e32 v18, v12
	v_mov_b32_e32 v19, v12
	v_readlane_b32 s44, v255, 21
	v_mov_b32_e32 v60, v4
	v_mov_b32_e32 v61, v5
	s_mov_b32 s6, 0x10000
	s_mov_b32 s7, 0
	global_load_dwordx4 v[64:67], v[60:61], off
	v_lshl_add_u64 v[60:61], v[60:61], 0, s[6:7]
	global_load_dwordx4 v[64:67], v[60:61], off
	v_lshl_add_u64 v[60:61], v[60:61], 0, s[6:7]
	global_load_dwordx4 v[64:67], v[60:61], off
	v_lshl_add_u64 v[60:61], v[60:61], 0, s[6:7]
	global_load_dwordx4 v[64:67], v[60:61], off
	v_lshl_add_u64 v[60:61], v[60:61], 0, s[6:7]
	global_load_dwordx4 v[64:67], v[60:61], off
	v_lshl_add_u64 v[60:61], v[60:61], 0, s[6:7]
	global_load_dwordx4 v[64:67], v[60:61], off
	v_lshl_add_u64 v[60:61], v[60:61], 0, s[6:7]
	global_load_dwordx4 v[64:67], v[60:61], off
	v_lshl_add_u64 v[60:61], v[60:61], 0, s[6:7]
	global_load_dwordx4 v[64:67], v[60:61], off
	v_lshl_add_u64 v[60:61], v[60:61], 0, s[6:7]
	global_load_dwordx4 v[64:67], v[60:61], off
	v_lshl_add_u64 v[60:61], v[60:61], 0, s[6:7]
	global_load_dwordx4 v[64:67], v[60:61], off
	v_lshl_add_u64 v[60:61], v[60:61], 0, s[6:7]
	global_load_dwordx4 v[64:67], v[60:61], off
	v_lshl_add_u64 v[60:61], v[60:61], 0, s[6:7]
	global_load_dwordx4 v[64:67], v[60:61], off
	v_lshl_add_u64 v[60:61], v[60:61], 0, s[6:7]
	global_load_dwordx4 v[64:67], v[60:61], off
	v_lshl_add_u64 v[60:61], v[60:61], 0, s[6:7]
	global_load_dwordx4 v[64:67], v[60:61], off
	v_lshl_add_u64 v[60:61], v[60:61], 0, s[6:7]
	global_load_dwordx4 v[64:67], v[60:61], off
	v_lshl_add_u64 v[60:61], v[60:61], 0, s[6:7]
	global_load_dwordx4 v[64:67], v[60:61], off
	v_lshl_add_u64 v[60:61], v[60:61], 0, s[6:7]
	global_load_dwordx4 v[64:67], v[60:61], off
	v_lshl_add_u64 v[60:61], v[60:61], 0, s[6:7]
	global_load_dwordx4 v[64:67], v[60:61], off
